# stack of small edits on the best kernel: K-loop edge rotation (4 GEMMs) + cache-hot trailing re-reads (P7/P9) + barrier leader no longer waits for the ack of its own release atomic
# speedup vs baseline: 1.0038x; 1.0017x over previous
; __device__ __forceinline__ unsigned xb_ld(unsigned* p)              { return __hip_atomic_load(p, __ATOMIC_RELAXED, __HIP_MEMORY_SCOPE_AGENT); }
; #define XB_SPIN(cond, bar) do { unsigned _sp = 0; while (cond) { __builtin_amdgcn_s_sleep(1); \
;     if ((++_sp & 255u) == 0u) { if (xb_ld(&(bar)[XB_TMO])) break; if (_sp > XB_SPIN_CAP) { atomicAdd(&(bar)[XB_TMO], 1u); break; } } } } while (0)
; __device__ __forceinline__ void xcd_barrier(const XcdBarrier& b) {
;     ...
;             asm volatile("s_waitcnt vmcnt(0)" ::: "memory");
;         } else {
;             XB_SPIN(xb_ld(&bar[XB_XGEN(b.x)]) == gen, bar);
;             __builtin_amdgcn_fence(__ATOMIC_ACQUIRE, "agent");
;             asm volatile("s_waitcnt vmcnt(0)" ::: "memory");
;         }
;     }
;     __syncthreads();
; __global__ void __launch_bounds__(NT, 2) fwd_kernel(Args args) {
;     ...
;         const int b = bl >> 6;
; #pragma unroll
;         for (int i8 = 0; i8 < 8; ++i8) { const int i = tid + NT * i8; const int which = i >> 10, d = i & 1023, r = (which < 2) ? b : 4, e = (which & 1) * 1024 + d;
;             float s = b_mod[e];
; #pragma unroll
;             for (int ks = 0; ks < 8; ++ks) s += MODP[(size_t)(ks * 5 + r) * 6144 + e];
;             T[i] = s; }
.LBB0_96:
	s_or_b64 exec, exec, s[12:13]
.LBB0_97:
	s_or_b64 exec, exec, s[4:5]
	s_add_u32 s24, s78, 0xe00000
	s_waitcnt lgkmcnt(0)
	v_mov_b32_e32 v1, v0
	s_addc_u32 s25, s79, 0
	s_barrier
	s_ashr_i32 s0, s2, 6
	s_movk_i32 s1, 0x800
	v_and_b32_e32 v2, 0x7ff, v1
	v_mov_b32_e32 v28, s0
	v_cmp_gt_i32_e32 vcc, s1, v1
	v_lshlrev_b32_e32 v18, 2, v2
	v_mov_b32_e32 v19, 0
	v_cndmask_b32_e32 v20, 4, v28, vcc
	v_lshl_add_u64 v[4:5], s[6:7], 0, v[18:19]
	s_movk_i32 s0, 0x6000
	v_mad_i64_i32 v[2:3], s[4:5], v20, s0, v[4:5]
	v_add_u32_e32 v6, 5, v20
	v_add_u32_e32 v8, 10, v20
	v_add_u32_e32 v10, 15, v20
	v_add_u32_e32 v12, 20, v20
	v_add_u32_e32 v14, 25, v20
	v_add_u32_e32 v16, 30, v20
	v_add_u32_e32 v20, 35, v20
	v_mad_i64_i32 v[6:7], s[4:5], v6, s0, v[4:5]
	v_mad_i64_i32 v[8:9], s[4:5], v8, s0, v[4:5]
	v_mad_i64_i32 v[10:11], s[4:5], v10, s0, v[4:5]
	v_mad_i64_i32 v[12:13], s[4:5], v12, s0, v[4:5]
	v_mad_i64_i32 v[14:15], s[4:5], v14, s0, v[4:5]
	v_mad_i64_i32 v[16:17], s[4:5], v16, s0, v[4:5]
	v_mad_i64_i32 v[20:21], s[4:5], v20, s0, v[4:5]
	global_load_dword v29, v[2:3], off
	global_load_dword v30, v[6:7], off
	global_load_dword v31, v[8:9], off
	global_load_dword v32, v[10:11], off
	global_load_dword v33, v[12:13], off
	global_load_dword v34, v[14:15], off
	global_load_dword v35, v[16:17], off
	global_load_dword v36, v[20:21], off
	v_add_u32_e32 v2, 0x200, v1
	s_movk_i32 s3, 0x600
	v_cmp_gt_i32_e32 vcc, s3, v1
	v_and_b32_e32 v2, 0x7ff, v2
	v_lshlrev_b32_e32 v2, 2, v2
	v_cndmask_b32_e32 v24, 4, v28, vcc
	v_mov_b32_e32 v3, v19
	v_lshl_add_u64 v[6:7], s[6:7], 0, v[2:3]
	v_add_u32_e32 v3, 5, v24
	v_mad_i64_i32 v[10:11], s[4:5], v3, s0, v[6:7]
	v_add_u32_e32 v3, 10, v24
	v_mad_i64_i32 v[12:13], s[4:5], v3, s0, v[6:7]
	v_add_u32_e32 v3, 15, v24
	v_mad_i64_i32 v[14:15], s[4:5], v3, s0, v[6:7]
	v_add_u32_e32 v3, 20, v24
	v_mad_i64_i32 v[16:17], s[4:5], v3, s0, v[6:7]
	v_add_u32_e32 v3, 25, v24
	v_mad_i64_i32 v[20:21], s[4:5], v3, s0, v[6:7]
	v_add_u32_e32 v3, 30, v24
	v_mad_i64_i32 v[22:23], s[4:5], v3, s0, v[6:7]
	v_add_u32_e32 v3, 35, v24
	v_mad_i64_i32 v[8:9], s[4:5], v24, s0, v[6:7]
	v_mad_i64_i32 v[6:7], s[4:5], v3, s0, v[6:7]
	s_movk_i32 s3, 0x400
	v_add_u32_e32 v3, 0x400, v1
	v_cmp_gt_i32_e32 vcc, s3, v1
	v_and_b32_e32 v3, 0x7ff, v3
	global_load_dword v37, v[8:9], off
	global_load_dword v38, v[10:11], off
	global_load_dword v39, v[12:13], off
	global_load_dword v40, v[14:15], off
	global_load_dword v41, v[16:17], off
	global_load_dword v42, v[20:21], off
	global_load_dword v43, v[22:23], off
	global_load_dword v44, v[6:7], off
	v_cndmask_b32_e32 v26, 4, v28, vcc
	v_lshlrev_b32_e32 v6, 2, v3
	v_mov_b32_e32 v7, v19
	v_lshl_add_u64 v[8:9], s[6:7], 0, v[6:7]
	v_add_u32_e32 v3, 5, v26
	v_mad_i64_i32 v[12:13], s[4:5], v3, s0, v[8:9]
	v_add_u32_e32 v3, 10, v26
	v_mad_i64_i32 v[14:15], s[4:5], v3, s0, v[8:9]
	v_add_u32_e32 v3, 15, v26
	v_mad_i64_i32 v[16:17], s[4:5], v3, s0, v[8:9]
	v_add_u32_e32 v3, 20, v26
	v_mad_i64_i32 v[20:21], s[4:5], v3, s0, v[8:9]
	v_add_u32_e32 v3, 25, v26
	v_mad_i64_i32 v[22:23], s[4:5], v3, s0, v[8:9]
	v_add_u32_e32 v3, 30, v26
	v_mad_i64_i32 v[24:25], s[4:5], v3, s0, v[8:9]
	v_add_u32_e32 v3, 35, v26
	s_movk_i32 s1, 0x200
	v_mad_i64_i32 v[10:11], s[4:5], v26, s0, v[8:9]
	v_mad_i64_i32 v[8:9], s[4:5], v3, s0, v[8:9]
	v_add_u32_e32 v3, 0x600, v1
	v_cmp_gt_i32_e32 vcc, s1, v1
	v_and_b32_e32 v3, 0x7ff, v3
	global_load_dword v45, v[10:11], off
	global_load_dword v46, v[12:13], off
	global_load_dword v47, v[14:15], off
	global_load_dword v48, v[16:17], off
	global_load_dword v49, v[20:21], off
	global_load_dword v50, v[22:23], off
	global_load_dword v51, v[24:25], off
	global_load_dword v52, v[8:9], off
	v_cndmask_b32_e32 v7, 4, v28, vcc
	v_lshlrev_b32_e32 v8, 2, v3
	v_mov_b32_e32 v9, v19
	v_lshl_add_u64 v[10:11], s[6:7], 0, v[8:9]
	v_add_u32_e32 v3, 5, v7
	v_mad_i64_i32 v[14:15], s[4:5], v3, s0, v[10:11]
	v_add_u32_e32 v3, 10, v7
	v_mad_i64_i32 v[16:17], s[4:5], v3, s0, v[10:11]
	v_add_u32_e32 v3, 15, v7
	v_mad_i64_i32 v[20:21], s[4:5], v3, s0, v[10:11]
	v_add_u32_e32 v3, 20, v7
	v_mad_i64_i32 v[22:23], s[4:5], v3, s0, v[10:11]
	v_add_u32_e32 v3, 25, v7
	v_mad_i64_i32 v[24:25], s[4:5], v3, s0, v[10:11]
	v_add_u32_e32 v3, 30, v7
	v_mad_i64_i32 v[26:27], s[4:5], v3, s0, v[10:11]
	v_add_u32_e32 v3, 35, v7
	v_cmp_gt_i32_e32 vcc, 0, v1
	v_mad_i64_i32 v[12:13], s[4:5], v7, s0, v[10:11]
	v_mad_i64_i32 v[10:11], s[4:5], v3, s0, v[10:11]
	v_cndmask_b32_e32 v3, 4, v28, vcc
	v_add_u32_e32 v7, 5, v3
	global_load_dword v53, v[12:13], off
	global_load_dword v54, v[14:15], off
	global_load_dword v55, v[16:17], off
	global_load_dword v56, v[20:21], off
	global_load_dword v57, v[22:23], off
	s_nop 0
	global_load_dword v24, v[24:25], off
	s_nop 0
	global_load_dword v25, v[26:27], off
	s_nop 0
	global_load_dword v26, v[10:11], off
	v_mad_i64_i32 v[10:11], s[4:5], v7, s0, v[4:5]
	v_add_u32_e32 v7, 10, v3
	v_mad_i64_i32 v[12:13], s[4:5], v7, s0, v[4:5]
	v_add_u32_e32 v7, 15, v3
	v_readlane_b32 s80, v240, 11
	v_mad_i64_i32 v[14:15], s[4:5], v7, s0, v[4:5]
	v_add_u32_e32 v7, 20, v3
	v_readlane_b32 s90, v240, 21
	v_readlane_b32 s91, v240, 22
	v_mad_i64_i32 v[16:17], s[4:5], v7, s0, v[4:5]
	v_add_u32_e32 v7, 25, v3
	s_nop 2
	global_load_dword v27, v18, s[90:91]
	global_load_dword v58, v8, s[90:91]
	global_load_dword v59, v18, s[90:91]
	v_mad_i64_i32 v[8:9], s[4:5], v3, s0, v[4:5]
	v_mad_i64_i32 v[20:21], s[4:5], v7, s0, v[4:5]
	v_add_u32_e32 v7, 30, v3
	v_add_u32_e32 v3, 35, v3
	v_mad_i64_i32 v[22:23], s[4:5], v7, s0, v[4:5]
	v_mad_i64_i32 v[4:5], s[4:5], v3, s0, v[4:5]
	v_add_u32_e32 v3, 0xa00, v1
	s_movk_i32 s1, 0xfe00
	v_cmp_gt_i32_e32 vcc, s1, v1
; __global__ void __launch_bounds__(NT, 2) fwd_kernel(Args args) {
;     ...
;         const int b = bl >> 6;
; #pragma unroll
;         for (int i8 = 0; i8 < 8; ++i8) { const int i = tid + NT * i8; const int which = i >> 10, d = i & 1023, r = (which < 2) ? b : 4, e = (which & 1) * 1024 + d;
;             float s = b_mod[e];
; #pragma unroll
;             for (int ks = 0; ks < 8; ++ks) s += MODP[(size_t)(ks * 5 + r) * 6144 + e];
;             T[i] = s; }
;         if (bl < 60) { const int e5 = bl * NT + tid, r = e5 / 6144, e = e5 % 6144; float s = b_mod[e];
	v_and_b32_e32 v3, 0x7ff, v3
	v_lshlrev_b32_e32 v18, 2, v3
	v_cndmask_b32_e32 v66, 4, v28, vcc
	global_load_dword v60, v[8:9], off
	global_load_dword v61, v[10:11], off
	global_load_dword v62, v[12:13], off
	global_load_dword v63, v[14:15], off
	global_load_dword v64, v[16:17], off
	global_load_dword v65, v[20:21], off
	s_nop 0
	global_load_dword v22, v[22:23], off
	s_nop 0
	global_load_dword v23, v[4:5], off
	v_lshl_add_u64 v[4:5], s[6:7], 0, v[18:19]
	v_add_u32_e32 v3, 5, v66
	v_mad_i64_i32 v[8:9], s[4:5], v3, s0, v[4:5]
	v_add_u32_e32 v3, 10, v66
	v_mad_i64_i32 v[10:11], s[4:5], v3, s0, v[4:5]
	v_add_u32_e32 v3, 15, v66
	v_mad_i64_i32 v[12:13], s[4:5], v3, s0, v[4:5]
	v_add_u32_e32 v3, 20, v66
	v_mad_i64_i32 v[14:15], s[4:5], v3, s0, v[4:5]
	v_add_u32_e32 v3, 25, v66
	v_mad_i64_i32 v[16:17], s[4:5], v3, s0, v[4:5]
	v_add_u32_e32 v3, 30, v66
	v_mad_i64_i32 v[20:21], s[4:5], v3, s0, v[4:5]
	v_add_u32_e32 v3, 35, v66
	global_load_dword v67, v6, s[90:91]
	global_load_dword v68, v18, s[90:91]
	v_mad_i64_i32 v[6:7], s[4:5], v66, s0, v[4:5]
	v_mad_i64_i32 v[4:5], s[4:5], v3, s0, v[4:5]
	v_add_u32_e32 v3, 0xc00, v1
	v_and_b32_e32 v3, 0x7ff, v3
	global_load_dword v66, v[6:7], off
	global_load_dword v69, v[8:9], off
	global_load_dword v70, v[10:11], off
	global_load_dword v71, v[12:13], off
	global_load_dword v72, v[14:15], off
	global_load_dword v73, v[16:17], off
	s_nop 0
	global_load_dword v20, v[20:21], off
	s_nop 0
	global_load_dword v21, v[4:5], off
	v_lshlrev_b32_e32 v18, 2, v3
	global_load_dword v75, v2, s[90:91]
	global_load_dword v76, v18, s[90:91]
	s_movk_i32 s1, 0xfc00
	v_cmp_gt_i32_e32 vcc, s1, v1
	v_lshl_add_u64 v[2:3], s[6:7], 0, v[18:19]
	s_movk_i32 s1, 0xfa00
	v_cndmask_b32_e32 v74, 4, v28, vcc
	v_add_u32_e32 v6, 5, v74
	v_add_u32_e32 v8, 10, v74
	v_add_u32_e32 v10, 15, v74
	v_add_u32_e32 v12, 20, v74
	v_add_u32_e32 v14, 25, v74
	v_add_u32_e32 v16, 30, v74
	v_add_u32_e32 v18, 35, v74
	v_mad_i64_i32 v[4:5], s[4:5], v74, s0, v[2:3]
	v_mad_i64_i32 v[6:7], s[4:5], v6, s0, v[2:3]
	v_mad_i64_i32 v[8:9], s[4:5], v8, s0, v[2:3]
	v_mad_i64_i32 v[10:11], s[4:5], v10, s0, v[2:3]
	v_mad_i64_i32 v[12:13], s[4:5], v12, s0, v[2:3]
	v_mad_i64_i32 v[14:15], s[4:5], v14, s0, v[2:3]
	v_mad_i64_i32 v[16:17], s[4:5], v16, s0, v[2:3]
	v_mad_i64_i32 v[2:3], s[4:5], v18, s0, v[2:3]
	global_load_dword v74, v[4:5], off
	global_load_dword v77, v[6:7], off
	global_load_dword v78, v[8:9], off
	global_load_dword v79, v[10:11], off
	global_load_dword v80, v[12:13], off
	global_load_dword v81, v[14:15], off
	global_load_dword v82, v[16:17], off
	global_load_dword v83, v[2:3], off
	v_add_u32_e32 v2, 0xe00, v1
	v_and_b32_e32 v2, 0x7ff, v2
	v_lshlrev_b32_e32 v18, 2, v2
	global_load_dword v84, v18, s[90:91]
	v_cmp_gt_i32_e32 vcc, s1, v1
	v_lshl_add_u64 v[2:3], s[6:7], 0, v[18:19]
	v_readlane_b32 s81, v240, 12
	v_cndmask_b32_e32 v28, 4, v28, vcc
	v_add_u32_e32 v6, 5, v28
	v_add_u32_e32 v8, 10, v28
	v_add_u32_e32 v10, 15, v28
	v_add_u32_e32 v12, 20, v28
	v_add_u32_e32 v14, 25, v28
	v_add_u32_e32 v16, 30, v28
	v_add_u32_e32 v18, 35, v28
	v_mad_i64_i32 v[4:5], s[4:5], v28, s0, v[2:3]
	v_mad_i64_i32 v[6:7], s[4:5], v6, s0, v[2:3]
	v_mad_i64_i32 v[8:9], s[4:5], v8, s0, v[2:3]
	v_mad_i64_i32 v[10:11], s[4:5], v10, s0, v[2:3]
	v_mad_i64_i32 v[12:13], s[4:5], v12, s0, v[2:3]
	v_mad_i64_i32 v[14:15], s[4:5], v14, s0, v[2:3]
	v_mad_i64_i32 v[16:17], s[4:5], v16, s0, v[2:3]
	v_mad_i64_i32 v[2:3], s[0:1], v18, s0, v[2:3]
	global_load_dword v4, v[4:5], off
	s_nop 0
	global_load_dword v5, v[6:7], off
	s_nop 0
	global_load_dword v6, v[8:9], off
	global_load_dword v7, v[10:11], off
	s_nop 0
	global_load_dword v8, v[12:13], off
	global_load_dword v9, v[14:15], off
	global_load_dword v10, v[16:17], off
	s_nop 0
	global_load_dword v2, v[2:3], off
	s_waitcnt vmcnt(39)
	v_add_f32_e32 v3, v27, v29
	v_add_f32_e32 v3, v3, v30
	v_add_f32_e32 v3, v3, v31
	v_add_f32_e32 v3, v3, v32
	v_add_f32_e32 v3, v3, v33
	v_add_f32_e32 v3, v3, v34
	v_add_f32_e32 v3, v3, v35
	v_add_f32_e32 v3, v3, v36
	v_lshl_add_u32 v11, v1, 2, 0
	v_readlane_b32 s84, v240, 15
	v_readlane_b32 s85, v240, 16
	v_readlane_b32 s92, v240, 23
	v_readlane_b32 s93, v240, 24
	v_readlane_b32 s94, v240, 25
	v_readlane_b32 s95, v240, 26
	s_mov_b64 s[28:29], s[92:93]
	s_mov_b64 s[16:17], s[80:81]
	s_waitcnt vmcnt(18)
	v_add_f32_e32 v12, v75, v37
	v_add_f32_e32 v12, v12, v38
	v_add_f32_e32 v12, v12, v39
	v_add_f32_e32 v12, v12, v40
	v_add_f32_e32 v12, v12, v41
	v_add_f32_e32 v12, v12, v42
	v_add_f32_e32 v12, v12, v43
	v_add_f32_e32 v12, v12, v44
	ds_write2st64_b32 v11, v3, v12 offset1:8
	v_add_f32_e32 v3, v67, v45
	v_add_f32_e32 v12, v58, v53
	v_add_f32_e32 v3, v3, v46
	v_add_f32_e32 v12, v12, v54
	v_add_f32_e32 v3, v3, v47
	v_add_f32_e32 v12, v12, v55
	v_add_f32_e32 v3, v3, v48
	v_add_f32_e32 v12, v12, v56
	v_add_f32_e32 v3, v3, v49
	v_add_f32_e32 v12, v12, v57
	v_add_f32_e32 v3, v3, v50
	v_add_f32_e32 v12, v12, v24
	v_add_f32_e32 v3, v3, v51
	v_add_f32_e32 v12, v12, v25
	v_add_f32_e32 v3, v3, v52
	v_add_f32_e32 v12, v12, v26
	ds_write2st64_b32 v11, v3, v12 offset0:16 offset1:24
	v_add_f32_e32 v3, v59, v60
	v_add_f32_e32 v12, v68, v66
	v_add_f32_e32 v3, v3, v61
	v_add_f32_e32 v12, v12, v69
	v_add_f32_e32 v3, v3, v62
	v_add_f32_e32 v12, v12, v70
	v_add_f32_e32 v3, v3, v63
	v_add_f32_e32 v12, v12, v71
	v_add_f32_e32 v3, v3, v64
	v_add_f32_e32 v12, v12, v72
	v_add_f32_e32 v3, v3, v65
	v_add_f32_e32 v12, v12, v73
	v_add_f32_e32 v3, v3, v22
	v_add_f32_e32 v12, v12, v20
	v_add_f32_e32 v3, v3, v23
	v_add_f32_e32 v12, v12, v21
	ds_write2st64_b32 v11, v3, v12 offset0:32 offset1:40
	s_waitcnt vmcnt(16)
	v_add_f32_e32 v3, v76, v74
	s_waitcnt vmcnt(15)
	v_add_f32_e32 v3, v3, v77
	s_waitcnt vmcnt(14)
	v_add_f32_e32 v3, v3, v78
	s_waitcnt vmcnt(13)
	v_add_f32_e32 v3, v3, v79
	s_waitcnt vmcnt(12)
	v_add_f32_e32 v3, v3, v80
	s_waitcnt vmcnt(11)
	v_add_f32_e32 v3, v3, v81
	s_waitcnt vmcnt(10)
	v_add_f32_e32 v3, v3, v82
	s_mov_b64 s[20:21], s[84:85]
	v_readfirstlane_b32 s0, v1
	s_mov_b32 s22, 0
	s_waitcnt vmcnt(9)
	v_add_f32_e32 v3, v3, v83
	s_cmp_gt_i32 s2, 59
	s_waitcnt vmcnt(7)
	v_add_f32_e32 v4, v84, v4
	s_waitcnt vmcnt(6)
	v_add_f32_e32 v4, v4, v5
	s_waitcnt vmcnt(5)
	v_add_f32_e32 v4, v4, v6
	s_waitcnt vmcnt(4)
	v_add_f32_e32 v4, v4, v7
	s_waitcnt vmcnt(3)
	v_add_f32_e32 v4, v4, v8
	s_waitcnt vmcnt(2)
	v_add_f32_e32 v4, v4, v9
	s_waitcnt vmcnt(1)
	v_add_f32_e32 v4, v4, v10
	s_waitcnt vmcnt(0)
	v_add_f32_e32 v2, v4, v2
	v_readlane_b32 s82, v240, 13
	v_readlane_b32 s83, v240, 14
	v_readlane_b32 s86, v240, 17
	v_readlane_b32 s87, v240, 18
	v_readlane_b32 s88, v240, 19
	v_readlane_b32 s89, v240, 20
	s_mov_b64 s[30:31], s[94:95]
	ds_write2st64_b32 v11, v3, v2 offset0:48 offset1:56
	s_cbranch_scc1 .LBB0_99
; __global__ void __launch_bounds__(NT, 2) fwd_kernel(Args args) {
;     ...
;         if (bl < 60) { const int e5 = bl * NT + tid, r = e5 / 6144, e = e5 % 6144; float s = b_mod[e];
; #pragma unroll
;             for (int ks = 0; ks < 8; ++ks) s += MODP[(size_t)(ks * 5 + r) * 6144 + e];
;             MODF[e5] = s; }
	v_lshl_add_u32 v2, s2, 9, v1
	s_mov_b32 s1, 0x2aaaaaab
	v_mul_hi_i32 v3, v2, s1
	v_lshrrev_b32_e32 v4, 31, v3
	v_ashrrev_i32_e32 v3, 10, v3
	v_add_u32_e32 v3, v3, v4
	v_mul_i32_i24_e32 v4, 0x1800, v3
	v_sub_u32_e32 v4, v2, v4
	v_ashrrev_i32_e32 v5, 31, v4
	s_mov_b64 s[26:27], s[90:91]
	v_lshlrev_b64 v[4:5], 2, v[4:5]
	v_lshl_add_u64 v[6:7], s[26:27], 0, v[4:5]
	global_load_dword v18, v[6:7], off
	v_mul_hi_i32_i24_e32 v7, 0x6000, v3
	v_mul_i32_i24_e32 v6, 0x6000, v3
	v_add_u32_e32 v8, 5, v3
	v_add_u32_e32 v10, 10, v3
	v_add_u32_e32 v12, 15, v3
	v_add_u32_e32 v14, 20, v3
	v_add_u32_e32 v16, 25, v3
	v_add_u32_e32 v20, 30, v3
	v_add_u32_e32 v3, 35, v3
	v_lshl_add_u64 v[4:5], s[6:7], 0, v[4:5]
	v_mul_hi_i32_i24_e32 v9, 0x6000, v8
	v_mul_i32_i24_e32 v8, 0x6000, v8
	v_mul_hi_i32_i24_e32 v11, 0x6000, v10
	v_mul_i32_i24_e32 v10, 0x6000, v10
	v_mul_hi_i32_i24_e32 v13, 0x6000, v12
	v_mul_i32_i24_e32 v12, 0x6000, v12
	v_mul_hi_i32_i24_e32 v15, 0x6000, v14
	v_mul_i32_i24_e32 v14, 0x6000, v14
	v_mul_hi_i32_i24_e32 v17, 0x6000, v16
	v_mul_i32_i24_e32 v16, 0x6000, v16
	v_mul_hi_i32_i24_e32 v21, 0x6000, v20
	v_mul_i32_i24_e32 v20, 0x6000, v20
	v_mul_hi_i32_i24_e32 v23, 0x6000, v3
	v_mul_i32_i24_e32 v22, 0x6000, v3
	v_lshl_add_u64 v[6:7], v[4:5], 0, v[6:7]
	v_lshl_add_u64 v[8:9], v[4:5], 0, v[8:9]
	v_lshl_add_u64 v[10:11], v[4:5], 0, v[10:11]
	v_lshl_add_u64 v[12:13], v[4:5], 0, v[12:13]
	v_lshl_add_u64 v[14:15], v[4:5], 0, v[14:15]
	v_lshl_add_u64 v[16:17], v[4:5], 0, v[16:17]
	v_lshl_add_u64 v[20:21], v[4:5], 0, v[20:21]
	v_lshl_add_u64 v[4:5], v[4:5], 0, v[22:23]
	global_load_dword v6, v[6:7], off
	s_nop 0
	global_load_dword v7, v[8:9], off
	s_nop 0
	global_load_dword v8, v[10:11], off
	global_load_dword v9, v[12:13], off
	s_nop 0
	global_load_dword v10, v[14:15], off
	global_load_dword v11, v[16:17], off
	global_load_dword v12, v[20:21], off
	s_nop 0
	global_load_dword v4, v[4:5], off
	v_ashrrev_i32_e32 v3, 31, v2
	v_lshl_add_u64 v[2:3], v[2:3], 2, s[24:25]
	s_waitcnt vmcnt(7)
	v_add_f32_e32 v5, v18, v6
	s_waitcnt vmcnt(6)
	v_add_f32_e32 v5, v5, v7
	s_waitcnt vmcnt(5)
	v_add_f32_e32 v5, v5, v8
	s_waitcnt vmcnt(4)
	v_add_f32_e32 v5, v5, v9
	s_waitcnt vmcnt(3)
	v_add_f32_e32 v5, v5, v10
	s_waitcnt vmcnt(2)
	v_add_f32_e32 v5, v5, v11
	s_waitcnt vmcnt(1)
	v_add_f32_e32 v5, v5, v12
	s_waitcnt vmcnt(0)
	v_add_f32_e32 v4, v5, v4
	global_store_dword v[2:3], v4, off

; __device__ __forceinline__ unsigned xb_ld(unsigned* p)              { return __hip_atomic_load(p, __ATOMIC_RELAXED, __HIP_MEMORY_SCOPE_AGENT); }
; #define XB_SPIN(cond, bar) do { unsigned _sp = 0; while (cond) { __builtin_amdgcn_s_sleep(1); \
;     if ((++_sp & 255u) == 0u) { if (xb_ld(&(bar)[XB_TMO])) break; if (_sp > XB_SPIN_CAP) { atomicAdd(&(bar)[XB_TMO], 1u); break; } } } } while (0)
;     __host__ __device__ bool next(int i, Unit& u) const {
;         const long L = (long)i * G + c; if (L >= nwg) return false;
;         int wgid = (int)L; { const int q = nwg / NXCD, r = nwg % NXCD, xcd = wgid % NXCD, off = wgid / NXCD; wgid = (xcd < r ? xcd * (q + 1) : r * (q + 1) + (xcd - r) * q) + off; }
;         const int nig = WGM * nN, gid = wgid / nig, fm = gid * WGM, gsz = (nM - fm) < WGM ? (nM - fm) : WGM;
;         u.pm = fm + ((wgid % nig) % gsz); u.pn = (wgid % nig) / gsz; return true;
; __device__ __forceinline__ void xcd_barrier(const XcdBarrier& b) {
;     ...
;             asm volatile("s_waitcnt vmcnt(0)" ::: "memory");
;         } else {
;             XB_SPIN(xb_ld(&bar[XB_XGEN(b.x)]) == gen, bar);
;             __builtin_amdgcn_fence(__ATOMIC_ACQUIRE, "agent");
;             asm volatile("s_waitcnt vmcnt(0)" ::: "memory");
;         }
;     }
;     __syncthreads();
.LBB0_250:
	s_or_b64 exec, exec, s[12:13]
.LBB0_251:
	s_or_b64 exec, exec, s[4:5]
	v_mov_b32_e32 v10, v0
	s_cmpk_lt_i32 s2, 0x2ec
	s_waitcnt lgkmcnt(0)
	s_barrier
	s_cselect_b64 s[0:1], -1, 0
	s_cmpk_gt_i32 s2, 0x2eb
	v_readfirstlane_b32 s20, v10
	s_cbranch_scc1 .LBB0_257
	s_ashr_i32 s3, s2, 31
	s_lshr_b32 s3, s3, 29
	s_add_i32 s3, s2, s3
	s_and_b32 s4, s3, -8
	s_sub_i32 s6, s2, s4
	s_cmp_gt_i32 s6, 3
	s_cbranch_scc0 .LBB0_254
	s_mul_i32 s4, s6, 0x5d
	s_add_i32 s7, s4, 4
	s_cbranch_execz .LBB0_255
	s_branch .LBB0_256

; __device__ __forceinline__ unsigned xb_ld(unsigned* p)              { return __hip_atomic_load(p, __ATOMIC_RELAXED, __HIP_MEMORY_SCOPE_AGENT); }
; #define XB_SPIN(cond, bar) do { unsigned _sp = 0; while (cond) { __builtin_amdgcn_s_sleep(1); \
;     if ((++_sp & 255u) == 0u) { if (xb_ld(&(bar)[XB_TMO])) break; if (_sp > XB_SPIN_CAP) { atomicAdd(&(bar)[XB_TMO], 1u); break; } } } } while (0)
; __device__ __forceinline__ void xcd_barrier(const XcdBarrier& b) {
;     ...
;             asm volatile("s_waitcnt vmcnt(0)" ::: "memory");
;         } else {
;             XB_SPIN(xb_ld(&bar[XB_XGEN(b.x)]) == gen, bar);
;             __builtin_amdgcn_fence(__ATOMIC_ACQUIRE, "agent");
;             asm volatile("s_waitcnt vmcnt(0)" ::: "memory");
;         }
;     }
;     __syncthreads();
; __global__ void __launch_bounds__(NT, 2) fwd_kernel(Args args) {
;     ...
;         if (bl < 32) { const int idx = bl * NT + tid, b = idx >> 12, which = (idx >> 10) & 3, col = idx & 1023; const float* mf = MODF + (size_t)b * 6144; float v;
;             if (which == 0) v = mf[2048 + col] * g_mix_post[col]; else if (which == 1) v = g_ffn_pre[col] * (1.0f + mf[4096 + col]); else if (which == 2) v = mf[3072 + col]; else v = mf[5120 + col] * g_ffn_post[col];
;             COMB[idx] = v; }
.LBB0_364:
	s_or_b64 exec, exec, s[12:13]
.LBB0_365:
	s_or_b64 exec, exec, s[4:5]
	s_add_u32 s12, s78, 0xe40000
	s_addc_u32 s13, s79, 0
	s_waitcnt lgkmcnt(0)
	v_mov_b32_e32 v1, v0
	s_cmp_gt_i32 s2, 31
	s_barrier
	s_cbranch_scc1 .LBB0_379
	v_lshl_add_u32 v2, s2, 9, v1
	v_ashrrev_i32_e32 v1, 12, v2
	v_bfe_u32 v6, v2, 10, 2
	v_mul_hi_i32_i24_e32 v5, 0x6000, v1
	v_mul_i32_i24_e32 v4, 0x6000, v1
	v_and_b32_e32 v3, 0x3ff, v2
	v_lshl_add_u64 v[4:5], s[24:25], 0, v[4:5]
	v_cmp_lt_i32_e32 vcc, 1, v6
	s_and_saveexec_b64 s[0:1], vcc
	s_xor_b64 s[0:1], exec, s[0:1]
	s_cbranch_execz .LBB0_372
	v_cmp_lt_i32_e32 vcc, 2, v6
	s_and_saveexec_b64 s[4:5], vcc
	s_xor_b64 s[4:5], exec, s[4:5]
	s_cbranch_execz .LBB0_369
	v_lshlrev_b32_e32 v6, 2, v3
	v_mov_b32_e32 v7, 0
	v_lshl_add_u64 v[4:5], v[4:5], 0, v[6:7]
	v_add_co_u32_e32 v4, vcc, 0x5000, v4
	s_nop 1
	v_addc_co_u32_e32 v5, vcc, 0, v5, vcc
	global_load_dword v1, v[4:5], off
	global_load_dword v3, v6, s[54:55]
	s_waitcnt vmcnt(0)
	v_mul_f32_e32 v1, v1, v3

; __device__ __forceinline__ unsigned xb_ld(unsigned* p)              { return __hip_atomic_load(p, __ATOMIC_RELAXED, __HIP_MEMORY_SCOPE_AGENT); }
; #define XB_SPIN(cond, bar) do { unsigned _sp = 0; while (cond) { __builtin_amdgcn_s_sleep(1); \
;     if ((++_sp & 255u) == 0u) { if (xb_ld(&(bar)[XB_TMO])) break; if (_sp > XB_SPIN_CAP) { atomicAdd(&(bar)[XB_TMO], 1u); break; } } } } while (0)
; __device__ __forceinline__ void xcd_barrier(const XcdBarrier& b) {
;     ...
;             asm volatile("s_waitcnt vmcnt(0)" ::: "memory");
;         } else {
;             XB_SPIN(xb_ld(&bar[XB_XGEN(b.x)]) == gen, bar);
;             __builtin_amdgcn_fence(__ATOMIC_ACQUIRE, "agent");
;             asm volatile("s_waitcnt vmcnt(0)" ::: "memory");
;         }
;     }
;     __syncthreads();
; __global__ void __launch_bounds__(NT, 2) fwd_kernel(Args args) {
;     ...
;         _Pragma("unroll 1") for (int u = bl; u < 4 * NCH + 2 * NCH; u += GRID) {
;             if (u < 4 * NCH) gla_unit<0>(lds, u >> 2, u & 3, PROJ, GT, STG, DECG, OMIX, gla_norm);
;             else { const int v = u - 4 * NCH; ssd_unit<0>(lds, v >> 1, v & 1, PROJ, XBC, At, DTt, STS, DECS, OMIX, d_skip, ssd_norm); }
;         }
.LBB0_557:
	s_or_b64 exec, exec, s[8:9]
.LBB0_558:
	s_or_b64 exec, exec, s[4:5]
	s_add_u32 s36, s78, 0xc20000
	s_addc_u32 s37, s79, 0
	s_add_u32 s40, s78, 0xca8000
	s_addc_u32 s41, s79, 0
	s_add_u32 s30, s78, 0xb400000
	s_addc_u32 s31, s79, 0
	s_add_u32 s28, s78, 0xd600000
	s_addc_u32 s29, s79, 0
	s_cmpk_gt_i32 s2, 0x65f
	s_waitcnt lgkmcnt(0)
	s_barrier
	s_cbranch_scc1 .LBB0_623
	s_and_b32 s0, s2, 1
	s_and_b32 s1, s2, 3
	s_lshl_b32 s34, s0, 2
	s_lshl_b32 s3, s1, 7
	v_readlane_b32 s4, v240, 32
	s_add_u32 s44, s4, s3
	v_readlane_b32 s4, v240, 33
	s_addc_u32 s45, s4, 0
	s_lshl_b32 s4, s1, 8
	s_add_u32 s46, s36, s4
	s_addc_u32 s47, s37, 0
	s_lshl_b32 s35, s1, 1
	s_lshl_b32 s0, s0, 7
	s_add_u32 s52, s20, s0
	s_addc_u32 s53, s21, 0
	s_add_u32 s54, s18, s3
	s_addc_u32 s55, s19, 0
	s_add_u32 s56, s18, s4
	s_mov_b32 s43, 0
	s_addc_u32 s57, s19, 0
	v_mov_b32_e32 v3, 0
	s_movk_i32 s60, 0x600
	s_movk_i32 s61, 0x1000
	s_movk_i32 s62, 0x2000
	s_movk_i32 s63, 0x90
	s_add_i32 s64, 0, 0x1a400
	s_movk_i32 s65, 0x3000
	s_movk_i32 s66, 0x4000
	s_movk_i32 s67, 0x5000
	s_movk_i32 s68, 0x7000
	s_mov_b32 s69, 0x8000
	s_mov_b32 s70, 0x9000
	s_mov_b32 s71, 0xa000
	s_mov_b32 s72, 0xb000
	s_movk_i32 s73, 0x1680
	s_mov_b32 s74, 0xc000
	s_mov_b32 s75, 0xe000
	s_mov_b32 s80, 0xf000
	s_mov_b32 s81, 0x11000
	s_mov_b32 s82, 0x12000
	s_mov_b32 s83, 0x13000
	s_movk_i32 s84, 0xff
	s_add_i32 s85, 0, 0x14400
	s_mov_b32 s86, 0xb400
	s_add_i32 s87, 0, 0xb400
	v_mov_b32_e32 v1, 0x1680
	s_mov_b32 s88, s2
	s_branch .LBB0_562

; __device__ __forceinline__ unsigned xb_ld(unsigned* p)              { return __hip_atomic_load(p, __ATOMIC_RELAXED, __HIP_MEMORY_SCOPE_AGENT); }
; #define XB_SPIN(cond, bar) do { unsigned _sp = 0; while (cond) { __builtin_amdgcn_s_sleep(1); \
;     if ((++_sp & 255u) == 0u) { if (xb_ld(&(bar)[XB_TMO])) break; if (_sp > XB_SPIN_CAP) { atomicAdd(&(bar)[XB_TMO], 1u); break; } } } } while (0)
; __device__ __forceinline__ void xcd_barrier(const XcdBarrier& b) {
;     ...
;             asm volatile("s_waitcnt vmcnt(0)" ::: "memory");
;         } else {
;             XB_SPIN(xb_ld(&bar[XB_XGEN(b.x)]) == gen, bar);
;             __builtin_amdgcn_fence(__ATOMIC_ACQUIRE, "agent");
;             asm volatile("s_waitcnt vmcnt(0)" ::: "memory");
;         }
;     }
;     __syncthreads();
; __global__ void __launch_bounds__(NT, 2) fwd_kernel(Args args) {
;     ...
;         const int gt = bl * NT + tid;
;         if (gt < 65536) {
;             const int chain = gt >> 11, b = chain >> 3, h = (chain >> 1) & 3, d = chain & 1, e = 4 * (gt & 2047);
.LBB0_674:
	s_or_b64 exec, exec, s[8:9]
.LBB0_675:
	s_or_b64 exec, exec, s[4:5]
	s_waitcnt lgkmcnt(0)
	v_mov_b32_e32 v1, v0
	s_barrier
	s_mov_b32 s0, 0xffff
	v_lshl_add_u32 v2, s2, 9, v1
	v_cmp_lt_i32_e32 vcc, s0, v2
	v_lshlrev_b32_e32 v12, 3, v2
	s_and_saveexec_b64 s[0:1], vcc
	s_xor_b64 s[6:7], exec, s[0:1]
	s_cbranch_execz .LBB0_690
	v_add_u32_e32 v1, 0xffff0000, v2
	v_lshrrev_b32_e32 v8, 14, v1
	v_bfe_u32 v9, v2, 11, 3
	v_bfe_i32 v10, v2, 10, 1
	v_bfe_u32 v1, v2, 10, 1
	v_and_b32_e32 v2, 0x1ff8, v12
	v_mov_b32_e32 v3, 0
	v_lshl_add_u64 v[4:5], s[28:29], 0, v[2:3]
	v_lshlrev_b32_e32 v2, 2, v9
	v_lshl_add_u64 v[6:7], s[40:41], 0, v[2:3]
	v_mov_b32_e32 v2, 0x100
	v_lshl_add_u32 v2, v8, 2, v2
	v_lshlrev_b32_e32 v13, 6, v8
	v_or_b32_e32 v8, v1, v2
	v_add_u32_e32 v27, 1, v8
	v_sub_u32_e32 v8, v2, v1
	v_cmp_eq_u32_e64 s[4:5], 0, v1
	v_add_u32_e32 v47, 2, v8
	v_and_or_b32 v21, v10, 3, v2
	v_cndmask_b32_e64 v8, 0, 3, s[4:5]
	v_or_b32_e32 v51, v8, v2
	v_mov_b32_e32 v2, v3
	s_mov_b32 s8, 0
	v_lshl_or_b32 v55, v9, 1, v1
	s_movk_i32 s9, 0x43
	s_mov_b32 s3, -2
	v_mov_b64_e32 v[8:9], v[2:3]
	v_mov_b64_e32 v[10:11], v[2:3]
	s_branch .LBB0_678

; __device__ __forceinline__ unsigned xb_ld(unsigned* p)              { return __hip_atomic_load(p, __ATOMIC_RELAXED, __HIP_MEMORY_SCOPE_AGENT); }
; #define XB_SPIN(cond, bar) do { unsigned _sp = 0; while (cond) { __builtin_amdgcn_s_sleep(1); \
;     if ((++_sp & 255u) == 0u) { if (xb_ld(&(bar)[XB_TMO])) break; if (_sp > XB_SPIN_CAP) { atomicAdd(&(bar)[XB_TMO], 1u); break; } } } } while (0)
; __device__ __forceinline__ void xcd_barrier(const XcdBarrier& b) {
;     ...
;             asm volatile("s_waitcnt vmcnt(0)" ::: "memory");
;         } else {
;             XB_SPIN(xb_ld(&bar[XB_XGEN(b.x)]) == gen, bar);
;             __builtin_amdgcn_fence(__ATOMIC_ACQUIRE, "agent");
;             asm volatile("s_waitcnt vmcnt(0)" ::: "memory");
;         }
;     }
;     __syncthreads();
; __global__ void __launch_bounds__(NT, 2) fwd_kernel(Args args) {
;     ...
;     {
;         const bf16* XBC = R1;
;         _Pragma("unroll 1") for (int u = bl; u < 4 * NCHL; u += GRID) gla_unit<1>(lds, u >> 2, u & 3, PROJ, GT, STG, DECG, OMIX, gla_norm);
.LBB0_756:
	s_or_b64 exec, exec, s[8:9]
.LBB0_757:
	s_or_b64 exec, exec, s[4:5]
	s_cmpk_gt_i32 s2, 0x3ff
	s_waitcnt lgkmcnt(0)
	s_barrier
	s_cbranch_scc1 .LBB0_786
	s_and_b32 s0, s2, 3
	s_lshl_b32 s1, s0, 7
	v_readlane_b32 s3, v240, 32
	s_add_u32 s36, s3, s1
	v_readlane_b32 s3, v240, 33
	s_addc_u32 s37, s3, 0
	s_lshl_b32 s34, s0, 1
	s_lshl_b32 s3, s0, 8
	s_add_u32 s40, s76, s3
	s_addc_u32 s41, s77, 0
	s_add_u32 s0, s18, s1
	s_addc_u32 s1, s19, 0
	s_add_u32 s42, s18, s3
	s_addc_u32 s43, s19, 0
	v_mov_b32_e32 v93, 0
	s_movk_i32 s35, 0x1680
	v_mov_b64_e32 v[94:95], s[0:1]
	v_mov_b32_e32 v1, 0x1680
	s_movk_i32 s52, 0x1000
	s_movk_i32 s53, 0x2000
	s_movk_i32 s54, 0x4000
	s_movk_i32 s55, 0x5000
	s_movk_i32 s56, 0x7000
	s_mov_b32 s57, 0x8000
	s_mov_b32 s58, 0x9000
	s_mov_b32 s59, 0xb000
	s_mov_b32 s60, 0xc000
	s_mov_b32 s61, 0xe000
	s_mov_b32 s62, 0xf000
	s_mov_b32 s63, 0x11000
	s_mov_b32 s64, 0x10000
	s_mov_b32 s65, 0x12000
	s_mov_b32 s66, 0x13000
	s_mov_b32 s67, 0x15000
	s_movk_i32 s68, 0xff
	s_movk_i32 s69, 0x100
	s_add_i32 s70, 0, 0x14400
	s_movk_i32 s71, 0x3000
	s_mov_b32 s72, 0xa000
	s_movk_i32 s73, 0x90
	s_add_i32 s74, 0, 0x6c00
	s_add_i32 s75, 0, 0x2400
	s_add_i32 s80, 0, 0x4800
	v_mov_b32_e32 v112, 0x358637bd
	s_mov_b32 s81, 0x800000
	s_mov_b32 s82, s2
	s_branch .LBB0_760

; __device__ __forceinline__ unsigned xb_ld(unsigned* p)              { return __hip_atomic_load(p, __ATOMIC_RELAXED, __HIP_MEMORY_SCOPE_AGENT); }
; #define XB_SPIN(cond, bar) do { unsigned _sp = 0; while (cond) { __builtin_amdgcn_s_sleep(1); \
;     if ((++_sp & 255u) == 0u) { if (xb_ld(&(bar)[XB_TMO])) break; if (_sp > XB_SPIN_CAP) { atomicAdd(&(bar)[XB_TMO], 1u); break; } } } } while (0)
; __device__ __forceinline__ void xcd_barrier(const XcdBarrier& b) {
;     ...
;             asm volatile("s_waitcnt vmcnt(0)" ::: "memory");
;         } else {
;             XB_SPIN(xb_ld(&bar[XB_XGEN(b.x)]) == gen, bar);
;             __builtin_amdgcn_fence(__ATOMIC_ACQUIRE, "agent");
;             asm volatile("s_waitcnt vmcnt(0)" ::: "memory");
;         }
;     }
;     __syncthreads();
; __global__ void __launch_bounds__(NT, 2) fwd_kernel(Args args) {
;     ...
;         const unsigned poison = (__hip_atomic_load(ctlw, __ATOMIC_RELAXED, __HIP_MEMORY_SCOPE_AGENT) != 0u);
;         pg8::Gemm g{OMIX, Wout_t, MLAT, 1024, 1024}; pg8::StaticOrder S; S.init(MLAT, 1024, GRID, bl);
.LBB0_1010:
	s_or_b64 exec, exec, s[8:9]
.LBB0_1011:
	s_or_b64 exec, exec, s[4:5]
	s_waitcnt lgkmcnt(0)
	v_mov_b32_e32 v1, 0
	s_waitcnt vmcnt(2)
	v_mov_b32_e32 v2, v0
	s_barrier
	global_load_dword v1, v1, s[78:79] sc1
	v_mov_b32_e32 v148, v0
	s_cmpk_lt_i32 s2, 0x100
	s_cselect_b64 s[22:23], -1, 0
	s_cmpk_gt_i32 s2, 0xff
	v_readfirstlane_b32 s34, v148
	s_cbranch_scc1 .LBB0_1114
	s_ashr_i32 s13, s2, 31
	s_lshr_b32 s0, s13, 29
	s_add_i32 s4, s2, s0
	s_and_b32 s0, s4, -8
	s_sub_i32 s5, s2, s0
	s_cmp_gt_i32 s5, -1
	s_cbranch_scc0 .LBB0_1014
	s_lshl_b32 s3, s5, 5
	s_cbranch_execz .LBB0_1015
	s_branch .LBB0_1016

; #define PG8_BAR __builtin_amdgcn_s_barrier()
; __device__ __forceinline__ unsigned xb_ld(unsigned* p)              { return __hip_atomic_load(p, __ATOMIC_RELAXED, __HIP_MEMORY_SCOPE_AGENT); }
; template <class Epi, class Sched, bool ALIGN_EPI = false, bool SP2 = false>
; __device__ __forceinline__ void gemm_phase(PG8_LAS unsigned char* lds, const Gemm g, const Sched& S, const Epi& E) {
;     int tid_l_ = threadIdx.x; asm volatile("" : "+v"(tid_l_));
;     const int tid = tid_l_, wid = __builtin_amdgcn_readfirstlane(tid >> 6), lane = tid & 63, wr = wid >> 2, wc = wid & 3, fr = lane & 15, fq = lane >> 4;
;     const int K = g.K, nt = K / BK;
;     unsigned voffA[2], voffB[2];
; #pragma unroll
;     for (int i = 0; i < 2; ++i) { int R, C; stage_rc(tid * 16 + i * 8192, R, C); const int Rb = Epi::PERM ? ((R & ~31) + perm32(R & 31)) : R;
;         voffA[i] = (unsigned)(R * K + C) * 2u; voffB[i] = (unsigned)(Rb * K + C) * 2u; }
;     const size_t kstep = (size_t)(BK * 2);
;     const size_t hstep = (size_t)HALF * K * 2;
;     const size_t tstep = 2 * hstep;
;     const unsigned ldsw = (unsigned)wid * 1024u;
;     const int aoff = lds_byte(wr * 64 + fr, fq * 8), boff = lds_byte(wc * 32 + fr, fq * 8);
;     ...
;     Unit cur, nxt; int ui = 0;
;     if (!S.next(0, cur)) return;
;     f32x4 acc[2][2][4][2];
; #pragma unroll
;     for (int a = 0; a < 2; ++a)
; #pragma unroll
;         for (int b = 0; b < 2; ++b)
; #pragma unroll
;             for (int m = 0; m < 4; ++m)
; #pragma unroll
;                 for (int n = 0; n < 2; ++n) acc[a][b][m][n] = (f32x4){0.f, 0.f, 0.f, 0.f};
;     bf16x8 At[4][2], B0[2][2], B1[2][2];
;     const char* cA = (const char*)g.A + (size_t)cur.pm * tstep; const char* cB = (const char*)g.Bt + (size_t)cur.pn * tstep;
;     S.a_ready(cur);
;     if constexpr (SP2) {
;         PG8_STAGE(PG8_SB(0, 0), cB, voffB); PG8_STAGE(PG8_SB(0, 1), cB + hstep, voffB); PG8_STAGE(PG8_SA(0, 0), cA, voffA); PG8_STAGE(PG8_SA(0, 1), cA + hstep, voffA);
;         if (wr == 1) PG8_BAR;
; __device__ __forceinline__ void xcd_barrier(const XcdBarrier& b) {
;     ...
;             asm volatile("s_waitcnt vmcnt(0)" ::: "memory");
;         } else {
;             XB_SPIN(xb_ld(&bar[XB_XGEN(b.x)]) == gen, bar);
;             __builtin_amdgcn_fence(__ATOMIC_ACQUIRE, "agent");
;             asm volatile("s_waitcnt vmcnt(0)" ::: "memory");
;         }
;     }
;     __syncthreads();
.LBB0_1165:
	s_or_b64 exec, exec, s[8:9]
.LBB0_1166:
	s_or_b64 exec, exec, s[4:5]
	s_add_u32 s8, s78, 0xa000000
	s_addc_u32 s9, s79, 0
	v_mov_b32_e32 v11, v0
	s_waitcnt lgkmcnt(0)
	s_barrier
	s_cmpk_gt_i32 s2, 0x57f
	v_readfirstlane_b32 s0, v11
	s_cbranch_scc1 .LBB0_1182
	s_waitcnt vmcnt(0)
	v_lshlrev_b32_e32 v1, 4, v11
	v_add_u32_e32 v2, 0x2000, v1
	v_ashrrev_i32_e32 v3, 31, v2
	v_lshrrev_b32_e32 v3, 22, v3
	v_add_u32_e32 v3, v2, v3
	v_ashrrev_i32_e32 v10, 10, v3
	v_mul_i32_i24_e32 v3, 0x400, v10
	v_sub_u32_e32 v2, v2, v3
	v_lshrrev_b32_e32 v3, 4, v2
	v_bitop3_b32 v2, v3, v2, 32 bitop3:0x6c
	v_ashrrev_i32_e32 v3, 31, v2
	v_lshrrev_b32_e32 v3, 26, v3
	v_add_u32_e32 v3, v2, v3
	v_lshlrev_b32_e32 v4, 3, v10
	v_ashrrev_i32_e32 v12, 6, v3
	v_and_b32_e32 v4, -16, v4
	v_add_u32_e32 v4, v12, v4
	v_and_b32_e32 v5, 3, v12
	s_mov_b32 s4, 0x1fffe0
	v_lshrrev_b32_e32 v6, 2, v4
	v_lshlrev_b32_e32 v7, 1, v4
	v_and_b32_e32 v3, 0xc0, v3
	v_and_or_b32 v5, v4, s4, v5
	v_and_b32_e32 v6, 4, v6
	v_and_b32_e32 v7, 24, v7
	v_sub_u32_e32 v2, v2, v3
	v_mov_b32_e32 v3, 1
	v_or3_b32 v5, v5, v6, v7
	v_lshlrev_b32_e32 v6, 5, v10
	v_ashrrev_i16_sdwa v2, v3, sext(v2) dst_sel:DWORD dst_unused:UNUSED_PAD src0_sel:DWORD src1_sel:BYTE_0
	v_and_b32_e32 v6, 32, v6
	v_bfe_i32 v13, v2, 0, 16
	v_add_lshl_u32 v2, v6, v13, 1
	v_lshl_add_u32 v130, v5, 11, v2
	v_lshl_add_u32 v132, v4, 11, v2
	v_bfe_i32 v2, v11, 27, 1
	v_lshrrev_b32_e32 v2, 22, v2
	v_add_u32_e32 v2, v1, v2
	v_and_b32_e32 v2, 0xfffffc00, v2
	v_sub_u32_e32 v1, v1, v2
	v_lshrrev_b32_e32 v2, 4, v1
	v_ashrrev_i32_e32 v4, 31, v11
	v_bitop3_b32 v1, v2, v1, 32 bitop3:0x6c
	v_lshrrev_b32_e32 v4, 26, v4
	v_ashrrev_i32_e32 v2, 31, v1
	v_add_u32_e32 v4, v11, v4
	v_lshrrev_b32_e32 v2, 26, v2
	v_ashrrev_i32_e32 v15, 6, v4
	v_add_u32_e32 v2, v1, v2
	v_lshlrev_b32_e32 v4, 3, v15
	v_ashrrev_i32_e32 v14, 6, v2
	v_and_b32_e32 v4, -16, v4
	v_add_u32_e32 v4, v14, v4
	v_and_b32_e32 v5, 3, v14
	s_ashr_i32 s13, s2, 31
	v_and_or_b32 v5, v4, s4, v5
	s_lshr_b32 s4, s13, 29
	s_add_i32 s4, s2, s4
	s_ashr_i32 s3, s0, 6
	s_ashr_i32 s5, s4, 3
	s_and_b32 s4, s4, -8
	s_ashr_i32 s1, s0, 8
	s_lshl_b32 s12, s3, 10
	s_sub_i32 s4, s2, s4
	s_cmp_lt_i32 s4, 0
	s_movk_i32 s34, 0xb1
	s_cselect_b32 s6, s34, 0xb0
	s_mul_i32 s4, s4, s6
	s_add_i32 s4, s4, s5
	s_mul_hi_i32 s5, s4, 0x2e8ba2e9
	s_lshr_b32 s6, s5, 31
	s_ashr_i32 s5, s5, 5
	s_add_i32 s5, s5, s6
	s_lshl_b32 s6, s5, 3
	s_mulk_i32 s5, 0xb0
	s_sub_i32 s5, s4, s5
	s_sext_i32_i16 s4, s5
	s_bfe_u32 s4, s4, 0x3001c
	s_add_i32 s7, s5, s4
	s_sext_i32_i16 s4, s7
	s_and_b32 s7, s7, 0xfff8
	s_sub_i32 s5, s5, s7
	s_sext_i32_i16 s5, s5
	v_lshrrev_b32_e32 v6, 2, v4
	v_lshlrev_b32_e32 v7, 1, v4
	v_and_b32_e32 v2, 0xc0, v2
	s_lshr_b32 s4, s4, 3
	s_add_i32 s38, s6, s5
	v_and_b32_e32 v6, 4, v6
	v_and_b32_e32 v7, 24, v7
	v_sub_u32_e32 v1, v1, v2
	s_ashr_i32 s39, s38, 31
	s_bfe_i64 s[10:11], s[4:5], 0x100000
	v_or3_b32 v5, v5, v6, v7
	v_lshlrev_b32_e32 v6, 5, v15
	v_ashrrev_i16_sdwa v1, v3, sext(v1) dst_sel:DWORD dst_unused:UNUSED_PAD src0_sel:DWORD src1_sel:BYTE_0
	s_lshl_b64 s[6:7], s[38:39], 19
	s_lshl_b64 s[10:11], s[10:11], 19
	v_and_b32_e32 v6, 32, v6
	v_bfe_i32 v16, v1, 0, 16
	s_add_u32 s42, s24, s10
	v_add_lshl_u32 v1, v6, v16, 1
	s_addc_u32 s43, s25, s11
	s_add_i32 s35, s12, 0
	v_lshl_add_u32 v134, v5, 11, v1
	s_add_i32 m0, s35, 0x10000
	v_lshl_add_u32 v136, v4, 11, v1
	global_load_lds_dwordx4 v134, s[42:43]
	s_add_i32 m0, s35, 0x12000
	s_add_u32 s10, s42, 0x40000
	global_load_lds_dwordx4 v130, s[42:43]
	s_addc_u32 s11, s43, 0
	s_add_i32 m0, s35, 0x14000
	v_mov_b32_e32 v135, 0
	global_load_lds_dwordx4 v134, s[10:11]
	s_add_i32 m0, s35, 0x16000
	s_add_u32 s40, s20, s6
	s_addc_u32 s41, s21, s7
	s_add_i32 s39, s35, 0x2000
	global_load_lds_dwordx4 v130, s[10:11]
	s_mov_b32 m0, s35
	s_add_u32 s6, s40, 0x40000
	global_load_lds_dwordx4 v136, s[40:41]
	s_mov_b32 m0, s39
	s_addc_u32 s7, s41, 0
	s_add_i32 s46, s35, 0x4000
	global_load_lds_dwordx4 v132, s[40:41]
	s_mov_b32 m0, s46
	s_add_i32 s47, s35, 0x6000
	global_load_lds_dwordx4 v136, s[6:7]
	s_mov_b32 m0, s47
	v_mov_b32_e32 v131, v135
	global_load_lds_dwordx4 v132, s[6:7]
	v_mov_b32_e32 v137, v135
	v_mov_b32_e32 v133, v135
	s_cmp_eq_u32 s1, 1
	s_mov_b32 s7, 0
	v_lshl_add_u64 v[8:9], s[42:43], 0, v[134:135]
	v_lshl_add_u64 v[6:7], s[42:43], 0, v[130:131]
	v_lshl_add_u64 v[2:3], s[40:41], 0, v[136:137]
	s_cselect_b64 s[10:11], -1, 0
	s_cmp_lg_u32 s1, 1
	v_lshl_add_u64 v[4:5], s[40:41], 0, v[132:133]
	s_cbranch_scc1 .LBB0_1169
	s_barrier

; __device__ __forceinline__ unsigned xb_ld(unsigned* p)              { return __hip_atomic_load(p, __ATOMIC_RELAXED, __HIP_MEMORY_SCOPE_AGENT); }
; #define XB_SPIN(cond, bar) do { unsigned _sp = 0; while (cond) { __builtin_amdgcn_s_sleep(1); \
;     if ((++_sp & 255u) == 0u) { if (xb_ld(&(bar)[XB_TMO])) break; if (_sp > XB_SPIN_CAP) { atomicAdd(&(bar)[XB_TMO], 1u); break; } } } } while (0)
; __device__ __forceinline__ void xcd_barrier(const XcdBarrier& b) {
;     ...
;             asm volatile("s_waitcnt vmcnt(0)" ::: "memory");
;         } else {
;             XB_SPIN(xb_ld(&bar[XB_XGEN(b.x)]) == gen, bar);
;             __builtin_amdgcn_fence(__ATOMIC_ACQUIRE, "agent");
;             asm volatile("s_waitcnt vmcnt(0)" ::: "memory");
;         }
;     }
;     __syncthreads();
; __global__ void __launch_bounds__(NT, 2) fwd_kernel(Args args) {
;     ...
;         const unsigned poison = (__hip_atomic_load(ctlw, __ATOMIC_RELAXED, __HIP_MEMORY_SCOPE_AGENT) != 0u);
;         pg8::Gemm g{ACT, Wdn_t, MLAT, 1024, DFF}; pg8::StaticOrder S; S.init(MLAT, 1024, GRID, bl);
.LBB0_1237:
	s_or_b64 exec, exec, s[12:13]
.LBB0_1238:
	s_or_b64 exec, exec, s[4:5]
	s_waitcnt lgkmcnt(0)
	v_mov_b32_e32 v1, 0
	s_barrier
	global_load_dword v218, v1, s[78:79] sc1
	s_andn2_b64 vcc, exec, s[22:23]
	v_readfirstlane_b32 s30, v0
	s_cbranch_vccnz .LBB0_1305
	s_ashr_i32 s35, s2, 31
	s_lshr_b32 s0, s35, 29
	s_add_i32 s5, s2, s0
	s_and_b32 s0, s5, -8
	s_sub_i32 s3, s2, s0
	s_cmp_gt_i32 s3, -1
	s_cbranch_scc0 .LBB0_1241
	s_lshl_b32 s4, s3, 5
	s_ashr_i32 s1, s5, 3
	s_cbranch_execz .LBB0_1242
	s_branch .LBB0_1243
